# all hot MFMA loop heads (three GEMM K-loops and both attention tile loops) aligned to 64 bytes, later phases at original 8-byte phase
# speedup vs baseline: 1.0011x; 1.0011x over previous
; #define LAS __attribute__((address_space(3)))
;     ...
;     const int ql = lane & 31, hh = lane >> 5;
;     o0 = (f32x16){}; o1 = (f32x16){};
;     float m = -1e30f, lsum = 0.f;
;     const int i15 = lane & 15, G = (lane >> 4) & 1, ql4 = ql - 4 * hh;
;     f32x16 CL, CM, CR;
;     { const float sq = slope2 * (float)ql;
; #pragma unroll
;       for (int reg = 0; reg < 16; ++reg) { const float kb_ = slope2 * (float)((reg & 3) + 8 * (reg >> 2) + 4 * hh); CL[reg] = kb_; CR[reg] = -kb_; CM[reg] = -fabsf(kb_ - sq); } }
;     const LAS unsigned char* kb = Ks + (LDSFLAT ? 0 : (32 * w + ql) * 128); const int sw = LDSFLAT ? 0 : ((ql >> 1) & 7);
;     int koff[4];
; #pragma unroll
;     for (int ks = 0; ks < 4; ++ks) koff[ks] = LDSFLAT ? 0 : (((2 * ks + hh) ^ sw) << 4);
;     const int c0 = (2 * G + ((i15 & 3) >> 1)) ^ (((i15 >> 3) & 1) << 2);
;     const LAS unsigned char* vb0 = LDSFLAT ? Vs : Vs + (32 * w + 4 * hh + (i15 >> 2)) * 128 + (i15 & 1) * 8 + (c0 << 4);
;     const LAS unsigned char* vb1 = LDSFLAT ? Vs + 64 : Vs + (32 * w + 4 * hh + (i15 >> 2)) * 128 + (i15 & 1) * 8 + ((c0 ^ 4) << 4);
;     bf16x8 kf[4];
; #pragma unroll
;     for (int ks = 0; ks < 4; ++ks) kf[ks] = *(const LAS bf16x8*)(kb + koff[ks]);
; template <int MODE  >
; __device__ __forceinline__ void p2_attention(Frame& F) {
;     ...
;             if (cur.isB) {
;                 const int hq = cur.head + h;
;                 const float slope = exp2f(-0.5f * (float)(hq + 1));
.LBB0_311:
	s_mov_b64 s[76:77], -1
	s_andn2_b64 vcc, exec, s[42:43]
	v_add_u32_e32 v248, v241, v237
	v_add_u32_e32 v249, v241, v238
	v_add_u32_e32 v250, v241, v239
	v_add_u32_e32 v251, v241, v240
	s_cbranch_vccnz .LBB0_340
	v_readlane_b32 s40, v255, 39
	s_add_i32 s92, s5, s40
	s_add_i32 s72, s92, 1
	v_cvt_f32_i32_e32 v1, s72
	s_mov_b32 s40, 0xc2fc0000
	ds_read_b128 v[204:207], v248
	ds_read_b128 v[200:203], v249
	ds_read_b128 v[196:199], v250
	ds_read_b128 v[192:195], v251
	v_mov_b32_e32 v14, v0
	v_mul_f32_e32 v2, -0.5, v1
	v_cmp_gt_f32_e32 vcc, s40, v2
	v_mov_b32_e32 v2, 0x42800000
	s_and_b64 s[72:73], vcc, exec
	v_cndmask_b32_e32 v2, 0, v2, vcc
	v_fmac_f32_e32 v2, -0.5, v1
	v_exp_f32_e32 v1, v2
	s_cselect_b32 s72, 0xffffffc0, 0
	v_mov_b32_e32 v15, v0
	v_mov_b32_e32 v4, v0
	v_ldexp_f32 v1, v1, s72
	v_mul_f32_e32 v232, 0x3fb8aa3b, v1
	v_pk_mul_f32 v[96:97], v[232:233], v[214:215] op_sel_hi:[0,1]
	v_pk_mul_f32 v[98:99], v[232:233], v[216:217] op_sel_hi:[0,1]
	v_pk_mul_f32 v[100:101], v[232:233], v[218:219] op_sel_hi:[0,1]
	v_pk_mul_f32 v[102:103], v[232:233], v[220:221] op_sel_hi:[0,1]
	v_pk_mul_f32 v[104:105], v[232:233], v[222:223] op_sel_hi:[0,1]
	v_pk_mul_f32 v[106:107], v[232:233], v[224:225] op_sel_hi:[0,1]
	v_pk_mul_f32 v[108:109], v[232:233], v[226:227] op_sel_hi:[0,1]
	v_pk_mul_f32 v[110:111], v[232:233], v[228:229] op_sel_hi:[0,1]
	v_fma_f32 v64, -v232, v236, v96
	v_fma_f32 v65, -v232, v236, v97
	v_fma_f32 v66, -v232, v236, v98
	v_fma_f32 v67, -v232, v236, v99
	v_fma_f32 v68, -v232, v236, v100
	v_fma_f32 v69, -v232, v236, v101
	v_fma_f32 v70, -v232, v236, v102
	v_fma_f32 v71, -v232, v236, v103
	v_fma_f32 v72, -v232, v236, v104
	v_fma_f32 v73, -v232, v236, v105
	v_fma_f32 v74, -v232, v236, v106
	v_fma_f32 v75, -v232, v236, v107
	v_fma_f32 v76, -v232, v236, v108
	v_fma_f32 v1, -v232, v236, v109
	v_fma_f32 v2, -v232, v236, v110
	v_fma_f32 v3, -v232, v236, v111
	v_and_b32_e32 v129, 0x7fffffff, v3
	v_and_b32_e32 v128, 0x7fffffff, v2
	v_and_b32_e32 v131, 0x7fffffff, v1
	v_mov_b32_e32 v1, v0
	v_mov_b32_e32 v2, v0
	v_mov_b32_e32 v3, v0
	v_mov_b32_e32 v5, v0
	v_mov_b32_e32 v6, v0
	v_mov_b32_e32 v7, v0
	v_mov_b32_e32 v8, v0
	v_mov_b32_e32 v9, v0
	v_mov_b32_e32 v10, v0
	v_mov_b32_e32 v11, v0
	v_mov_b32_e32 v12, v0
	v_mov_b32_e32 v13, v0
	v_and_b32_e32 v130, 0x7fffffff, v76
	v_and_b32_e32 v133, 0x7fffffff, v75
	v_and_b32_e32 v132, 0x7fffffff, v74
	v_and_b32_e32 v135, 0x7fffffff, v73
	v_and_b32_e32 v134, 0x7fffffff, v72
	v_and_b32_e32 v137, 0x7fffffff, v71
	v_and_b32_e32 v136, 0x7fffffff, v70
	v_and_b32_e32 v139, 0x7fffffff, v69
	v_and_b32_e32 v138, 0x7fffffff, v68
	v_and_b32_e32 v141, 0x7fffffff, v67
	v_and_b32_e32 v140, 0x7fffffff, v66
	v_and_b32_e32 v143, 0x7fffffff, v65
	v_and_b32_e32 v142, 0x7fffffff, v64
	v_mov_b64_e32 v[78:79], v[14:15]
	v_mov_b64_e32 v[94:95], v[14:15]
	s_mov_b32 s91, 0
	v_xor_b32_e32 v114, 0x80000000, v98
	v_xor_b32_e32 v115, 0x80000000, v99
	v_xor_b32_e32 v116, 0x80000000, v100
	v_xor_b32_e32 v117, 0x80000000, v101
	v_xor_b32_e32 v118, 0x80000000, v102
	v_xor_b32_e32 v119, 0x80000000, v103
	v_xor_b32_e32 v120, 0x80000000, v104
	v_xor_b32_e32 v121, 0x80000000, v105
	v_xor_b32_e32 v122, 0x80000000, v106
	v_xor_b32_e32 v123, 0x80000000, v107
	v_xor_b32_e32 v124, 0x80000000, v108
	v_xor_b32_e32 v125, 0x80000000, v109
	v_xor_b32_e32 v126, 0x80000000, v110
	v_xor_b32_e32 v127, 0x80000000, v111
	v_xor_b32_e32 v113, 0x80000000, v97
	v_xor_b32_e32 v112, 0x80000000, v96
	v_mov_b32_e32 v252, 0xf149f2ca
	v_mov_b32_e32 v253, 0
	v_mov_b32_e32 v244, v233
	v_mov_b32_e32 v243, v234
	s_mov_b32 s93, 0
	v_mov_b64_e32 v[76:77], v[12:13]
	v_mov_b64_e32 v[74:75], v[10:11]
	v_mov_b64_e32 v[72:73], v[8:9]
	v_mov_b64_e32 v[70:71], v[6:7]
	v_mov_b64_e32 v[68:69], v[4:5]
	v_mov_b64_e32 v[66:67], v[2:3]
	v_mov_b64_e32 v[64:65], v[0:1]
	v_mov_b64_e32 v[92:93], v[12:13]
	v_mov_b64_e32 v[90:91], v[10:11]
	v_mov_b64_e32 v[88:89], v[8:9]
	v_mov_b64_e32 v[86:87], v[6:7]
	v_mov_b64_e32 v[84:85], v[4:5]
	v_mov_b64_e32 v[82:83], v[2:3]
	v_mov_b64_e32 v[80:81], v[0:1]
	v_readlane_b32 s41, v255, 40
	.p2align 6

; #define LAS __attribute__((address_space(3)))
;     ...
;     const int ql = lane & 31, hh = lane >> 5;
;     o0 = (f32x16){}; o1 = (f32x16){};
;     float m = -1e30f, lsum = 0.f;
;     const int i15 = lane & 15, G = (lane >> 4) & 1, ql4 = ql - 4 * hh;
;     f32x16 CL, CM, CR;
;     { const float sq = slope2 * (float)ql;
; #pragma unroll
;       for (int reg = 0; reg < 16; ++reg) { const float kb_ = slope2 * (float)((reg & 3) + 8 * (reg >> 2) + 4 * hh); CL[reg] = kb_; CR[reg] = -kb_; CM[reg] = -fabsf(kb_ - sq); } }
;     const LAS unsigned char* kb = Ks + (LDSFLAT ? 0 : (32 * w + ql) * 128); const int sw = LDSFLAT ? 0 : ((ql >> 1) & 7);
;     int koff[4];
; #pragma unroll
;     for (int ks = 0; ks < 4; ++ks) koff[ks] = LDSFLAT ? 0 : (((2 * ks + hh) ^ sw) << 4);
;     const int c0 = (2 * G + ((i15 & 3) >> 1)) ^ (((i15 >> 3) & 1) << 2);
;     const LAS unsigned char* vb0 = LDSFLAT ? Vs : Vs + (32 * w + 4 * hh + (i15 >> 2)) * 128 + (i15 & 1) * 8 + (c0 << 4);
;     const LAS unsigned char* vb1 = LDSFLAT ? Vs + 64 : Vs + (32 * w + 4 * hh + (i15 >> 2)) * 128 + (i15 & 1) * 8 + ((c0 ^ 4) << 4);
;     bf16x8 kf[4];
; #pragma unroll
;     for (int ks = 0; ks < 4; ++ks) kf[ks] = *(const LAS bf16x8*)(kb + koff[ks]);
.LBB0_342:
	ds_read_b128 v[140:143], v248
	ds_read_b128 v[136:139], v249
	ds_read_b128 v[132:135], v250
	ds_read_b128 v[128:131], v251
	v_mov_b32_e32 v14, v0
	v_mov_b32_e32 v15, v0
	v_mov_b32_e32 v1, v0
	v_mov_b32_e32 v2, v0
	v_mov_b32_e32 v3, v0
	v_mov_b32_e32 v4, v0
	v_mov_b32_e32 v5, v0
	v_mov_b32_e32 v6, v0
	v_mov_b32_e32 v7, v0
	v_mov_b32_e32 v8, v0
	v_mov_b32_e32 v9, v0
	v_mov_b32_e32 v10, v0
	v_mov_b32_e32 v11, v0
	v_mov_b32_e32 v12, v0
	v_mov_b32_e32 v13, v0
	v_mov_b64_e32 v[78:79], v[14:15]
	v_mov_b64_e32 v[94:95], v[14:15]
	s_mov_b32 s91, 0
	v_mov_b32_e32 v148, 0xf149f2ca
	v_mov_b32_e32 v149, 0
	v_mov_b32_e32 v150, v233
	v_mov_b32_e32 v151, v234
	v_mov_b64_e32 v[76:77], v[12:13]
	v_mov_b64_e32 v[74:75], v[10:11]
	v_mov_b64_e32 v[72:73], v[8:9]
	v_mov_b64_e32 v[70:71], v[6:7]
	v_mov_b64_e32 v[68:69], v[4:5]
	v_mov_b64_e32 v[66:67], v[2:3]
	v_mov_b64_e32 v[64:65], v[0:1]
	v_mov_b64_e32 v[92:93], v[12:13]
	v_mov_b64_e32 v[90:91], v[10:11]
	v_mov_b64_e32 v[88:89], v[8:9]
	v_mov_b64_e32 v[86:87], v[6:7]
	v_mov_b64_e32 v[84:85], v[4:5]
	v_mov_b64_e32 v[82:83], v[2:3]
	v_mov_b64_e32 v[80:81], v[0:1]
	s_mov_b32 s93, 0
	.p2align 6
